# y1 + LN1 loop: the 20 per-trip parameter vector loads issued together at the top of the trip (were 20 serialized L2 round trips)
# baseline (speedup 1.0000x reference)
; __device__ __forceinline__ float bf_lo(unsigned w) { return __uint_as_float(w << 16); }
; __device__ __forceinline__ float bf_hi(unsigned w) { return __uint_as_float(w & 0xffff0000u); }
; __device__ __forceinline__ const float* mod_ptr(unsigned char* ws, int l, int r) { const int v = r < T ? (r >> 13) : 4; return (const float*)(ws + WS_MOD) + (size_t)(l * 5 + v) * 6144; }
; __device__ __forceinline__ void ph_ln1_router(const Ctx& X, CArgs a, int l, int nrows) {
;     ...
;     for (int r0 = gw * 2; r0 < nrows; r0 += NGW * 2) {
;         const float* md = uni(mod_ptr(X.ws, l, r0));
;         unsigned l4 = 4u * (unsigned)X.lane; asm volatile("" : "+v"(l4));
;         float* x1p = uni(X1 + (size_t)r0 * D); unsigned char* h2p = uni(H2 + (size_t)r0 * D);
;         f32x4 v[2][4]; float s[2] = {0.f, 0.f};
; #pragma unroll
;         for (int j = 0; j < 4; ++j) { v[0][j] = xn[0][j]; v[1][j] = xn[1][j]; }
; #pragma unroll
;         for (int j = 0; j < 4; ++j) { const f32x4 g1 = *(const f32x4*)(md + (l4 + 2048u + 256u * j));
; #pragma unroll
;             for (int q = 0; q < 2; ++q) { const v2u ow = on[q][j]; const f32x4 of = {bf_lo(ow.x), bf_hi(ow.x), bf_lo(ow.y), bf_hi(ow.y)};
;                 v[q][j] = v[q][j] * DN_ALPHA + g1 * of;
;                 s[q] += (v[q][j][0] + v[q][j][1]) + (v[q][j][2] + v[q][j][3]); } }
;     ...
;         for (int j = 0; j < 4; ++j) { const unsigned c = l4 + 256u * j;
;             const f32x4 g4 = *(const f32x4*)(lg + c), b4 = *(const f32x4*)(lb + c), sc4 = *(const f32x4*)(md + (c + 4096u)) + 1.0f, sh4 = *(const f32x4*)(md + (c + 3072u));
.LBB0_1413:
	s_min_i32 s14, s24, 0x8000
	s_ashr_i32 s14, s14, 13
	s_add_i32 s14, s14, s44
	s_mul_hi_i32 s15, s14, 0x6000
	s_mulk_i32 s14, 0x6000
	s_add_u32 s26, s37, s14
	v_mov_b32_e32 v64, v108
	s_addc_u32 s27, s38, s15
	s_waitcnt vmcnt(7)
	v_lshlrev_b32_e32 v38, 16, v62
	v_add_u32_e32 v0, 0x800, v64
	s_waitcnt lgkmcnt(0)
	v_lshl_add_u64 v[34:35], v[0:1], 2, s[26:27]
	v_lshlrev_b32_e32 v129, 2, v64
	v_add_u32_e32 v126, 0x2000, v129
	v_add_u32_e32 v127, 0x3000, v129
	v_add_u32_e32 v128, 0x4000, v129
	global_load_dwordx4 v[154:157], v126, s[26:27]
	global_load_dwordx4 v[158:161], v126, s[26:27] offset:1024
	global_load_dwordx4 v[162:165], v126, s[26:27] offset:2048
	global_load_dwordx4 v[166:169], v126, s[26:27] offset:3072
	global_load_dwordx4 v[170:173], v128, s[26:27]
	global_load_dwordx4 v[174:177], v129, s[18:19]
	global_load_dwordx4 v[178:181], v129, s[20:21]
	global_load_dwordx4 v[182:185], v127, s[26:27]
	global_load_dwordx4 v[186:189], v128, s[26:27] offset:1024
	global_load_dwordx4 v[190:193], v129, s[18:19] offset:1024
	global_load_dwordx4 v[194:197], v129, s[20:21] offset:1024
	global_load_dwordx4 v[198:201], v127, s[26:27] offset:1024
	global_load_dwordx4 v[202:205], v128, s[26:27] offset:2048
	global_load_dwordx4 v[206:209], v129, s[18:19] offset:2048
	global_load_dwordx4 v[210:213], v129, s[20:21] offset:2048
	global_load_dwordx4 v[214:217], v127, s[26:27] offset:2048
	global_load_dwordx4 v[218:221], v128, s[26:27] offset:3072
	global_load_dwordx4 v[222:225], v129, s[18:19] offset:3072
	global_load_dwordx4 v[114:117], v129, s[20:21] offset:3072
	global_load_dwordx4 v[118:121], v127, s[26:27] offset:3072
	s_waitcnt vmcnt(16)
	s_nop 1
	v_mov_b64_e32 v[34:35], v[154:155]
	v_mov_b64_e32 v[36:37], v[156:157]
	v_and_b32_e32 v39, 0xffff0000, v62
	v_lshlrev_b32_e32 v40, 16, v63
	v_and_b32_e32 v41, 0xffff0000, v63
	s_mov_b32 s14, 0x3fb504f3
	v_lshlrev_b32_e32 v42, 16, v59
	v_and_b32_e32 v43, 0xffff0000, v59
	v_lshlrev_b32_e32 v44, 16, v61
	v_and_b32_e32 v45, 0xffff0000, v61
	v_lshlrev_b32_e32 v68, 16, v57
	v_and_b32_e32 v69, 0xffff0000, v57
	v_lshlrev_b32_e32 v70, 16, v55
	v_and_b32_e32 v71, 0xffff0000, v55
	v_lshlrev_b32_e32 v94, 16, v52
	v_and_b32_e32 v95, 0xffff0000, v52
	v_lshlrev_b32_e32 v96, 16, v53
	v_and_b32_e32 v97, 0xffff0000, v53
	s_mov_b32 s25, 0xf800000
	v_mov_b32_e32 v65, v1
	v_lshlrev_b64 v[106:107], 2, v[64:65]
	v_pk_mul_f32 v[40:41], v[36:37], v[40:41]
	v_pk_mul_f32 v[38:39], v[34:35], v[38:39]
	v_pk_fma_f32 v[86:87], v[4:5], s[14:15], v[40:41] op_sel_hi:[1,0,1]
	v_pk_fma_f32 v[88:89], v[2:3], s[14:15], v[38:39] op_sel_hi:[1,0,1]
	v_mov_b32_e32 v41, v87
	v_pk_mov_b32 v[38:39], v[88:89], v[86:87] op_sel:[1,0]
	v_mov_b32_e32 v40, v88
	v_pk_add_f32 v[38:39], v[38:39], v[40:41]
	v_pk_mul_f32 v[36:37], v[36:37], v[42:43]
	v_add_f32_e32 v0, v38, v39
	v_lshlrev_b32_e32 v38, 16, v58
	v_and_b32_e32 v39, 0xffff0000, v58
	v_pk_mul_f32 v[34:35], v[34:35], v[38:39]
	v_pk_fma_f32 v[66:67], v[8:9], s[14:15], v[36:37] op_sel_hi:[1,0,1]
	v_pk_fma_f32 v[72:73], v[6:7], s[14:15], v[34:35] op_sel_hi:[1,0,1]
	v_mov_b32_e32 v37, v67
	v_pk_mov_b32 v[34:35], v[72:73], v[66:67] op_sel:[1,0]
	v_mov_b32_e32 v36, v72
	v_pk_add_f32 v[34:35], v[34:35], v[36:37]
	v_add_f32_e32 v40, 0, v0
	v_add_f32_e32 v0, v34, v35
	v_add_f32_e32 v38, 0, v0
	v_add_u32_e32 v0, 0x900, v64
	v_lshl_add_u64 v[34:35], v[0:1], 2, s[26:27]
	s_nop 1
	v_mov_b64_e32 v[34:35], v[158:159]
	v_mov_b64_e32 v[36:37], v[160:161]
	v_lshlrev_b32_e32 v42, 16, v60
	v_and_b32_e32 v43, 0xffff0000, v60
	v_add_u32_e32 v0, 0xa00, v64
	v_pk_mul_f32 v[44:45], v[36:37], v[44:45]
	v_pk_mul_f32 v[42:43], v[34:35], v[42:43]
	v_pk_fma_f32 v[84:85], v[12:13], s[14:15], v[44:45] op_sel_hi:[1,0,1]
	v_pk_fma_f32 v[82:83], v[10:11], s[14:15], v[42:43] op_sel_hi:[1,0,1]
	v_mov_b32_e32 v45, v85
	v_pk_mov_b32 v[42:43], v[82:83], v[84:85] op_sel:[1,0]
	v_mov_b32_e32 v44, v82
	v_pk_add_f32 v[42:43], v[42:43], v[44:45]
	v_pk_mul_f32 v[36:37], v[36:37], v[68:69]
	v_pk_add_f32 v[44:45], v[42:43], v[42:43] op_sel:[0,1] op_sel_hi:[1,0]
	v_lshlrev_b32_e32 v42, 16, v56
	v_and_b32_e32 v43, 0xffff0000, v56
	v_pk_mul_f32 v[34:35], v[34:35], v[42:43]
	v_pk_fma_f32 v[76:77], v[16:17], s[14:15], v[36:37] op_sel_hi:[1,0,1]
	v_pk_fma_f32 v[74:75], v[14:15], s[14:15], v[34:35] op_sel_hi:[1,0,1]
	v_mov_b32_e32 v37, v77
	v_pk_mov_b32 v[34:35], v[74:75], v[76:77] op_sel:[1,0]
	v_mov_b32_e32 v36, v74
	v_pk_add_f32 v[34:35], v[34:35], v[36:37]
	v_lshlrev_b32_e32 v68, 16, v54
	v_pk_add_f32 v[42:43], v[34:35], v[34:35] op_sel:[0,1] op_sel_hi:[1,0]
	v_lshl_add_u64 v[34:35], v[0:1], 2, s[26:27]
	s_nop 1
	v_mov_b64_e32 v[34:35], v[162:163]
	v_mov_b64_e32 v[36:37], v[164:165]
	v_and_b32_e32 v69, 0xffff0000, v54
	v_add_u32_e32 v0, 0xb00, v64
	v_pk_mul_f32 v[68:69], v[34:35], v[68:69]
	v_pk_mul_f32 v[70:71], v[36:37], v[70:71]
	v_pk_fma_f32 v[78:79], v[18:19], s[14:15], v[68:69] op_sel_hi:[1,0,1]
	v_lshlrev_b32_e32 v68, 16, v50
	v_and_b32_e32 v69, 0xffff0000, v50
	v_pk_fma_f32 v[80:81], v[20:21], s[14:15], v[70:71] op_sel_hi:[1,0,1]
	v_lshlrev_b32_e32 v70, 16, v51
	v_and_b32_e32 v71, 0xffff0000, v51
	v_pk_mul_f32 v[34:35], v[34:35], v[68:69]
	v_pk_mul_f32 v[36:37], v[36:37], v[70:71]
	v_pk_fma_f32 v[68:69], v[22:23], s[14:15], v[34:35] op_sel_hi:[1,0,1]
	v_lshl_add_u64 v[34:35], v[0:1], 2, s[26:27]
	v_pk_fma_f32 v[70:71], v[24:25], s[14:15], v[36:37] op_sel_hi:[1,0,1]
	s_nop 1
	v_mov_b64_e32 v[34:35], v[166:167]
	v_mov_b64_e32 v[36:37], v[168:169]
	v_add_f32_e32 v90, v78, v79
	v_add_f32_e32 v92, v80, v81
	v_add_f32_e32 v98, v68, v69
	v_add_f32_e32 v100, v70, v71
	v_pk_mul_f32 v[96:97], v[36:37], v[96:97]
	v_pk_mul_f32 v[94:95], v[34:35], v[94:95]
	v_pk_fma_f32 v[96:97], v[28:29], s[14:15], v[96:97] op_sel_hi:[1,0,1]
	v_pk_fma_f32 v[94:95], v[26:27], s[14:15], v[94:95] op_sel_hi:[1,0,1]
	v_mov_b32_e32 v91, v96
	v_mov_b32_e32 v41, v94
	v_mov_b32_e32 v45, v95
	v_mov_b32_e32 v93, v97
	v_pk_add_f32 v[40:41], v[40:41], v[44:45]
	v_pk_add_f32 v[44:45], v[90:91], v[92:93]
	s_nop 0
	v_pk_add_f32 v[40:41], v[40:41], v[44:45]
	v_lshlrev_b32_e32 v44, 16, v49
	v_add_f32_e32 v0, v40, v41
	v_lshlrev_b32_e32 v40, 16, v48
	v_and_b32_e32 v41, 0xffff0000, v48
	v_and_b32_e32 v45, 0xffff0000, v49
	v_pk_mul_f32 v[36:37], v[36:37], v[44:45]
	v_pk_mul_f32 v[34:35], v[34:35], v[40:41]
	v_pk_fma_f32 v[90:91], v[32:33], s[14:15], v[36:37] op_sel_hi:[1,0,1]
	v_pk_fma_f32 v[92:93], v[30:31], s[14:15], v[34:35] op_sel_hi:[1,0,1]
	v_mov_b32_e32 v99, v90
	v_mov_b32_e32 v39, v92
	v_mov_b32_e32 v43, v93
	v_mov_b32_e32 v101, v91
	v_pk_add_f32 v[34:35], v[38:39], v[42:43]
	v_pk_add_f32 v[36:37], v[98:99], v[100:101]
	v_mov_b32_e32 v99, v1
	v_pk_add_f32 v[34:35], v[34:35], v[36:37]
	s_nop 0
	v_add_f32_e32 v34, v34, v35
	s_waitcnt lgkmcnt(0)
; __device__ __forceinline__ void ph_ln1_router(const Ctx& X, CArgs a, int l, int nrows) {
;     ...
;         float mean[2], rstd[2];
; #pragma unroll
;         for (int q = 0; q < 2; ++q) mean[q] = wave_sum(s[q]) * (1.0f / D);
; #pragma unroll
;         for (int q = 0; q < 2; ++q) { float qq = 0.f;
; #pragma unroll
;             for (int j = 0; j < 4; ++j) { v[q][j] = v[q][j] - mean[q]; qq += (v[q][j][0] * v[q][j][0] + v[q][j][1] * v[q][j][1]) + (v[q][j][2] * v[q][j][2] + v[q][j][3] * v[q][j][3]); }
;             s[q] = qq; }
; #pragma unroll
;         for (int q = 0; q < 2; ++q) rstd[q] = 1.0f / sqrtf(wave_sum(s[q]) * (1.0f / D) + LN_EPS);
	s_nop 1
	v_add_f32_dpp v0, v0, v0 quad_perm:[1,0,3,2] row_mask:0xf bank_mask:0xf
	s_waitcnt lgkmcnt(0)
	s_nop 1
	v_add_f32_dpp v0, v0, v0 quad_perm:[2,3,0,1] row_mask:0xf bank_mask:0xf
	s_waitcnt lgkmcnt(0)
	s_nop 1
	v_add_f32_dpp v0, v0, v0 row_half_mirror row_mask:0xf bank_mask:0xf
	s_waitcnt lgkmcnt(0)
	s_nop 1
	v_add_f32_dpp v0, v0, v0 row_mirror row_mask:0xf bank_mask:0xf
	v_mov_b32_e32 v35, v0
	s_waitcnt lgkmcnt(0)
	s_nop 1
	v_permlane16_swap_b32_e32 v0, v35
	v_add_f32_e32 v0, v0, v35
	v_mov_b32_e32 v35, v0
	s_waitcnt lgkmcnt(0)
	s_nop 1
	v_permlane32_swap_b32_e32 v0, v35
	v_add_f32_e32 v42, v0, v35
	v_fmamk_f32 v89, v42, 0xba800000, v89
	v_fmac_f32_e32 v88, 0xba800000, v42
	v_fmamk_f32 v87, v42, 0xba800000, v87
	v_fmac_f32_e32 v86, 0xba800000, v42
	s_waitcnt lgkmcnt(0)
	s_nop 1
	v_add_f32_dpp v0, v34, v34 quad_perm:[1,0,3,2] row_mask:0xf bank_mask:0xf
	v_pk_mul_f32 v[36:37], v[88:89], v[88:89]
	v_fmamk_f32 v83, v42, 0xba800000, v83
	v_fmac_f32_e32 v82, 0xba800000, v42
	v_fmamk_f32 v85, v42, 0xba800000, v85
	s_waitcnt lgkmcnt(0)
	s_nop 1
	v_add_f32_dpp v0, v0, v0 quad_perm:[2,3,0,1] row_mask:0xf bank_mask:0xf
	v_fmac_f32_e32 v84, 0xba800000, v42
	v_fmac_f32_e32 v78, 0xba800000, v42
	v_fmamk_f32 v79, v42, 0xba800000, v79
	v_fmac_f32_e32 v80, 0xba800000, v42
	s_waitcnt lgkmcnt(0)
	s_nop 1
	v_add_f32_dpp v0, v0, v0 row_half_mirror row_mask:0xf bank_mask:0xf
	v_fmamk_f32 v81, v42, 0xba800000, v81
	v_fmamk_f32 v97, v42, 0xba800000, v97
	v_fmac_f32_e32 v96, 0xba800000, v42
	v_fmamk_f32 v95, v42, 0xba800000, v95
	s_waitcnt lgkmcnt(0)
	s_nop 1
	v_add_f32_dpp v0, v0, v0 row_mirror row_mask:0xf bank_mask:0xf
	v_mov_b32_e32 v34, v0
	v_fmac_f32_e32 v94, 0xba800000, v42
	s_waitcnt lgkmcnt(0)
	s_nop 1
	v_permlane16_swap_b32_e32 v0, v34
	v_add_f32_e32 v0, v0, v34
	v_mov_b32_e32 v34, v0
	s_waitcnt lgkmcnt(0)
	s_nop 1
	v_permlane32_swap_b32_e32 v0, v34
	v_add_f32_e32 v43, v0, v34
	v_pk_mul_f32 v[34:35], v[86:87], v[86:87]
	v_mul_f32_e32 v0, v78, v78
	v_pk_mov_b32 v[38:39], v[36:37], v[34:35] op_sel:[1,0]
	v_mov_b32_e32 v37, v35
	v_pk_add_f32 v[34:35], v[38:39], v[36:37]
	v_pk_mul_f32 v[36:37], v[84:85], v[84:85]
	v_pk_mul_f32 v[38:39], v[82:83], v[82:83]
	v_pk_add_f32 v[34:35], v[34:35], v[34:35] op_sel_hi:[0,1]
	v_pk_mov_b32 v[40:41], v[38:39], v[36:37] op_sel:[1,0]
	v_mov_b32_e32 v39, v37
	v_pk_add_f32 v[36:37], v[40:41], v[38:39]
	v_pk_fma_f32 v[38:39], v[78:79], v[78:79], v[0:1] op_sel_hi:[1,1,0]
	v_mul_f32_e32 v0, v80, v80
	v_pk_add_f32 v[36:37], v[36:37], v[36:37] op_sel_hi:[0,1]
	v_pk_fma_f32 v[40:41], v[80:81], v[80:81], v[0:1] op_sel_hi:[1,1,0]
	v_mul_f32_e32 v38, v94, v94
	v_mul_f32_e32 v40, v95, v95
	v_mul_f32_e32 v34, v96, v96
	v_mul_f32_e32 v36, v97, v97
	v_pk_add_f32 v[38:39], v[38:39], v[40:41]
	v_pk_add_f32 v[34:35], v[34:35], v[36:37]
	v_fmamk_f32 v73, v43, 0xba800000, v73
	v_pk_add_f32 v[34:35], v[38:39], v[34:35]
	v_fmac_f32_e32 v72, 0xba800000, v43
	v_fmamk_f32 v67, v43, 0xba800000, v67
	v_fmac_f32_e32 v66, 0xba800000, v43
	v_add_f32_e32 v42, v34, v35
	v_pk_mul_f32 v[34:35], v[66:67], v[66:67]
	v_pk_mul_f32 v[36:37], v[72:73], v[72:73]
	v_fmamk_f32 v75, v43, 0xba800000, v75
	v_pk_mov_b32 v[38:39], v[36:37], v[34:35] op_sel:[1,0]
	v_mov_b32_e32 v37, v35
	v_fmac_f32_e32 v74, 0xba800000, v43
	v_fmamk_f32 v77, v43, 0xba800000, v77
	v_fmac_f32_e32 v76, 0xba800000, v43
	v_pk_add_f32 v[34:35], v[38:39], v[36:37]
	v_pk_mul_f32 v[36:37], v[76:77], v[76:77]
	v_pk_mul_f32 v[38:39], v[74:75], v[74:75]
	v_fmac_f32_e32 v68, 0xba800000, v43
	v_pk_mov_b32 v[40:41], v[38:39], v[36:37] op_sel:[1,0]
	v_mov_b32_e32 v39, v37
	v_fmamk_f32 v69, v43, 0xba800000, v69
	v_fmac_f32_e32 v70, 0xba800000, v43
	v_mul_f32_e32 v0, v68, v68
	v_pk_add_f32 v[36:37], v[40:41], v[38:39]
	v_fmamk_f32 v71, v43, 0xba800000, v71
	v_pk_fma_f32 v[38:39], v[68:69], v[68:69], v[0:1] op_sel_hi:[1,1,0]
	v_mul_f32_e32 v0, v70, v70
	v_pk_add_f32 v[34:35], v[34:35], v[34:35] op_sel_hi:[0,1]
	v_pk_add_f32 v[36:37], v[36:37], v[36:37] op_sel_hi:[0,1]
	v_pk_fma_f32 v[40:41], v[70:71], v[70:71], v[0:1] op_sel_hi:[1,1,0]
	v_fmamk_f32 v91, v43, 0xba800000, v91
	v_fmac_f32_e32 v90, 0xba800000, v43
	v_fmamk_f32 v93, v43, 0xba800000, v93
	v_fmac_f32_e32 v92, 0xba800000, v43
	v_mul_f32_e32 v38, v92, v92
	v_mul_f32_e32 v40, v93, v93
	v_mul_f32_e32 v34, v90, v90
	v_mul_f32_e32 v36, v91, v91
	v_pk_add_f32 v[38:39], v[38:39], v[40:41]
	v_pk_add_f32 v[34:35], v[34:35], v[36:37]
	s_nop 0
	v_pk_add_f32 v[34:35], v[38:39], v[34:35]
	s_nop 0
	v_add_f32_e32 v0, v34, v35
	s_waitcnt lgkmcnt(0)
	s_nop 1
	v_add_f32_dpp v34, v42, v42 quad_perm:[1,0,3,2] row_mask:0xf bank_mask:0xf
	s_waitcnt lgkmcnt(0)
	s_nop 1
	v_add_f32_dpp v34, v34, v34 quad_perm:[2,3,0,1] row_mask:0xf bank_mask:0xf
	s_waitcnt lgkmcnt(0)
	s_nop 1
	v_add_f32_dpp v34, v34, v34 row_half_mirror row_mask:0xf bank_mask:0xf
	s_waitcnt lgkmcnt(0)
	s_nop 1
	v_add_f32_dpp v34, v34, v34 row_mirror row_mask:0xf bank_mask:0xf
	v_mov_b32_e32 v35, v34
	s_waitcnt lgkmcnt(0)
	s_nop 1
	v_permlane16_swap_b32_e32 v34, v35
	v_add_f32_e32 v34, v34, v35
	v_mov_b32_e32 v35, v34
	s_waitcnt lgkmcnt(0)
; __device__ __forceinline__ unsigned pk_fp8x4(float a, float b, float c, float d) { int w = 0; w = __builtin_amdgcn_cvt_pk_fp8_f32(clamp448(a), clamp448(b), w, false); w = __builtin_amdgcn_cvt_pk_fp8_f32(clamp448(c), clamp448(d), w, true); return (unsigned)w; }
; __device__ __forceinline__ void ph_ln1_router(const Ctx& X, CArgs a, int l, int nrows) {
;     ...
;         for (int q = 0; q < 2; ++q) rstd[q] = 1.0f / sqrtf(wave_sum(s[q]) * (1.0f / D) + LN_EPS);
; #pragma unroll
;         for (int j = 0; j < 4; ++j) { const unsigned c = l4 + 256u * j;
;             const f32x4 g4 = *(const f32x4*)(lg + c), b4 = *(const f32x4*)(lb + c), sc4 = *(const f32x4*)(md + (c + 4096u)) + 1.0f, sh4 = *(const f32x4*)(md + (c + 3072u));
; #pragma unroll
;             for (int q = 0; q < 2; ++q) { const f32x4 y = v[q][j] * rstd[q] * g4 + b4;
;                 *(f32x4*)(x1p + (c + 1024u * q)) = y;
;                 const f32x4 h = y * sc4 + sh4; v[q][j] = h;
;                 *(unsigned*)(h2p + (c + 1024u * q)) = pg8::pk_fp8x4(h[0], h[1], h[2], h[3]); } }
	s_nop 1
	v_permlane32_swap_b32_e32 v34, v35
	v_add_f32_e32 v34, v34, v35
	v_fmamk_f32 v34, v34, 0x3a800000, v239
	v_cmp_gt_f32_e32 vcc, s25, v34
	v_mul_f32_e32 v35, 0x4f800000, v34
	s_nop 0
	v_cndmask_b32_e32 v34, v34, v35, vcc
	v_sqrt_f32_e32 v35, v34
	s_nop 0
	v_add_u32_e32 v36, -1, v35
	v_fma_f32 v37, -v36, v35, v34
	v_cmp_ge_f32_e64 s[14:15], 0, v37
	v_add_u32_e32 v37, 1, v35
	s_nop 0
	v_cndmask_b32_e64 v36, v35, v36, s[14:15]
	v_fma_f32 v35, -v37, v35, v34
	v_cmp_lt_f32_e64 s[14:15], 0, v35
	s_nop 1
	v_cndmask_b32_e64 v35, v36, v37, s[14:15]
	v_mul_f32_e32 v36, 0x37800000, v35
	v_cndmask_b32_e32 v35, v35, v36, vcc
	v_cmp_class_f32_e32 vcc, v34, v238
	s_nop 1
	v_cndmask_b32_e32 v34, v35, v34, vcc
	v_div_scale_f32 v35, s[14:15], v34, v34, 1.0
	v_rcp_f32_e32 v36, v35
	s_nop 0
	v_fma_f32 v37, -v35, v36, 1.0
	v_fmac_f32_e32 v36, v37, v36
	v_div_scale_f32 v37, vcc, 1.0, v34, 1.0
	v_mul_f32_e32 v38, v37, v36
	v_fma_f32 v39, -v35, v38, v37
	v_fmac_f32_e32 v38, v39, v36
	v_fma_f32 v35, -v35, v38, v37
	v_div_fmas_f32 v35, v35, v36, v38
	v_div_fixup_f32 v100, v35, v34, 1.0
	v_pk_mul_f32 v[88:89], v[88:89], v[100:101] op_sel_hi:[1,0]
	v_pk_mul_f32 v[86:87], v[86:87], v[100:101] op_sel_hi:[1,0]
	s_waitcnt lgkmcnt(0)
	s_nop 1
	v_add_f32_dpp v0, v0, v0 quad_perm:[1,0,3,2] row_mask:0xf bank_mask:0xf
	s_waitcnt lgkmcnt(0)
	s_nop 1
	v_add_f32_dpp v0, v0, v0 quad_perm:[2,3,0,1] row_mask:0xf bank_mask:0xf
	s_waitcnt lgkmcnt(0)
	s_nop 1
	v_add_f32_dpp v0, v0, v0 row_half_mirror row_mask:0xf bank_mask:0xf
	s_waitcnt lgkmcnt(0)
	s_nop 1
	v_add_f32_dpp v0, v0, v0 row_mirror row_mask:0xf bank_mask:0xf
	v_mov_b32_e32 v34, v0
	s_waitcnt lgkmcnt(0)
	s_nop 1
	v_permlane16_swap_b32_e32 v0, v34
	v_add_f32_e32 v0, v0, v34
	v_mov_b32_e32 v34, v0
	s_waitcnt lgkmcnt(0)
	s_nop 1
	v_permlane32_swap_b32_e32 v0, v34
	v_add_f32_e32 v0, v0, v34
	v_fmamk_f32 v0, v0, 0x3a800000, v239
	v_cmp_gt_f32_e32 vcc, s25, v0
	v_mul_f32_e32 v34, 0x4f800000, v0
	s_nop 0
	v_cndmask_b32_e32 v0, v0, v34, vcc
	v_sqrt_f32_e32 v34, v0
	s_nop 0
	v_add_u32_e32 v35, -1, v34
	v_fma_f32 v36, -v35, v34, v0
	v_cmp_ge_f32_e64 s[14:15], 0, v36
	v_add_u32_e32 v36, 1, v34
	s_nop 0
	v_cndmask_b32_e64 v35, v34, v35, s[14:15]
	v_fma_f32 v34, -v36, v34, v0
	v_cmp_lt_f32_e64 s[14:15], 0, v34
	s_nop 1
	v_cndmask_b32_e64 v34, v35, v36, s[14:15]
	v_mul_f32_e32 v35, 0x37800000, v34
	v_cndmask_b32_e32 v34, v34, v35, vcc
	v_cmp_class_f32_e32 vcc, v0, v238
	s_nop 1
	v_cndmask_b32_e32 v0, v34, v0, vcc
	v_div_scale_f32 v34, s[14:15], v0, v0, 1.0
	v_rcp_f32_e32 v35, v34
	s_nop 0
	v_fma_f32 v36, -v34, v35, 1.0
	v_fmac_f32_e32 v35, v36, v35
	v_div_scale_f32 v36, vcc, 1.0, v0, 1.0
	v_mul_f32_e32 v37, v36, v35
	v_fma_f32 v38, -v34, v37, v36
	v_fmac_f32_e32 v37, v38, v35
	v_fma_f32 v34, -v34, v37, v36
	v_div_fmas_f32 v34, v34, v35, v37
	v_div_fixup_f32 v98, v34, v0, 1.0
	v_add_u32_e32 v0, 0x1000, v64
	v_lshl_add_u64 v[42:43], v[0:1], 2, s[26:27]
	s_waitcnt vmcnt(0)
	s_nop 1
	v_mov_b64_e32 v[42:43], v[170:171]
	v_mov_b64_e32 v[44:45], v[172:173]
	v_lshl_add_u64 v[34:35], s[18:19], 0, v[106:107]
	v_lshl_add_u64 v[38:39], s[20:21], 0, v[106:107]
	v_add_u32_e32 v0, 0xc00, v64
	s_nop 1
	v_mov_b64_e32 v[34:35], v[174:175]
	v_mov_b64_e32 v[36:37], v[176:177]
	v_pk_add_f32 v[102:103], v[42:43], 1.0 op_sel_hi:[1,0]
	s_nop 1
	v_mov_b64_e32 v[38:39], v[178:179]
	v_mov_b64_e32 v[40:41], v[180:181]
	v_lshl_add_u64 v[42:43], v[0:1], 2, s[26:27]
	v_pk_add_f32 v[104:105], v[44:45], 1.0 op_sel_hi:[1,0]
	s_nop 1
	v_mov_b64_e32 v[42:43], v[182:183]
	v_mov_b64_e32 v[44:45], v[184:185]
	v_pk_fma_f32 v[110:111], v[34:35], v[88:89], v[38:39]
	v_pk_fma_f32 v[112:113], v[36:37], v[86:87], v[40:41]
	v_lshl_add_u64 v[86:87], s[2:3], 0, v[106:107]
	v_pk_fma_f32 v[88:89], v[102:103], v[110:111], v[42:43]
	global_store_dwordx4 v[86:87], v[110:113], off
	v_med3_f32 v0, v88, s59, v250
	v_med3_f32 v65, v89, s59, v250
	v_cvt_pk_fp8_f32 v99, v0, v65
	v_pk_fma_f32 v[86:87], v[104:105], v[112:113], v[44:45]
	s_nop 0
	v_med3_f32 v0, v86, s59, v250
	v_med3_f32 v65, v87, s59, v250
	v_cvt_pk_fp8_f32 v99, v0, v65 op_sel:[0,0,1]
	v_add_u32_e32 v0, 0x400, v64
	v_pk_mul_f32 v[72:73], v[72:73], v[98:99] op_sel_hi:[1,0]
	v_pk_mul_f32 v[66:67], v[66:67], v[98:99] op_sel_hi:[1,0]
	v_pk_fma_f32 v[34:35], v[34:35], v[72:73], v[38:39]
	v_pk_fma_f32 v[36:37], v[36:37], v[66:67], v[40:41]
	v_lshl_add_u64 v[38:39], v[0:1], 2, s[2:3]
	v_pk_fma_f32 v[72:73], v[102:103], v[34:35], v[42:43]
	global_store_dword v64, v99, s[22:23]
	global_store_dwordx4 v[38:39], v[34:37], off
	v_pk_fma_f32 v[66:67], v[104:105], v[36:37], v[44:45]
	v_add_u32_e32 v42, 0x1100, v64
	v_med3_f32 v34, v72, s59, v250
	v_med3_f32 v35, v73, s59, v250
	v_mov_b32_e32 v36, v1
	v_cvt_pk_fp8_f32 v36, v34, v35
	v_med3_f32 v34, v66, s59, v250
	v_med3_f32 v35, v67, s59, v250
	v_mov_b32_e32 v43, v1
	v_cvt_pk_fp8_f32 v36, v34, v35 op_sel:[0,0,1]
	v_lshl_add_u64 v[42:43], v[42:43], 2, s[26:27]
	v_pk_mul_f32 v[68:69], v[68:69], v[98:99] op_sel_hi:[1,0]
	v_pk_mul_f32 v[70:71], v[70:71], v[98:99] op_sel_hi:[1,0]
	global_store_dword v0, v36, s[22:23]
	s_nop 1
	v_mov_b64_e32 v[42:43], v[186:187]
	v_mov_b64_e32 v[44:45], v[188:189]
	v_add_u32_e32 v0, 0x100, v64
	v_lshlrev_b64 v[106:107], 2, v[0:1]
	v_lshl_add_u64 v[34:35], s[18:19], 0, v[106:107]
	v_lshl_add_u64 v[38:39], s[20:21], 0, v[106:107]
	s_nop 1
	v_mov_b64_e32 v[34:35], v[190:191]
	v_mov_b64_e32 v[36:37], v[192:193]
	v_pk_mul_f32 v[92:93], v[92:93], v[98:99] op_sel_hi:[1,0]
	s_nop 1
	v_mov_b64_e32 v[38:39], v[194:195]
	v_mov_b64_e32 v[40:41], v[196:197]
	v_pk_mul_f32 v[90:91], v[90:91], v[98:99] op_sel_hi:[1,0]
	v_pk_add_f32 v[112:113], v[42:43], 1.0 op_sel_hi:[1,0]
; __device__ __forceinline__ unsigned pk_fp8x4(float a, float b, float c, float d) { int w = 0; w = __builtin_amdgcn_cvt_pk_fp8_f32(clamp448(a), clamp448(b), w, false); w = __builtin_amdgcn_cvt_pk_fp8_f32(clamp448(c), clamp448(d), w, true); return (unsigned)w; }
; __device__ __forceinline__ void ph_ln1_router(const Ctx& X, CArgs a, int l, int nrows) {
;     ...
;         for (int j = 0; j < 4; ++j) { const unsigned c = l4 + 256u * j;
;             const f32x4 g4 = *(const f32x4*)(lg + c), b4 = *(const f32x4*)(lb + c), sc4 = *(const f32x4*)(md + (c + 4096u)) + 1.0f, sh4 = *(const f32x4*)(md + (c + 3072u));
; #pragma unroll
;             for (int q = 0; q < 2; ++q) { const f32x4 y = v[q][j] * rstd[q] * g4 + b4;
;                 *(f32x4*)(x1p + (c + 1024u * q)) = y;
;                 const f32x4 h = y * sc4 + sh4; v[q][j] = h;
;                 *(unsigned*)(h2p + (c + 1024u * q)) = pg8::pk_fp8x4(h[0], h[1], h[2], h[3]); } }
;         __builtin_amdgcn_sched_barrier(0);
;         if (r0 + NGW * 2 < nrows) LN1_FETCH(r0 + NGW * 2);
	v_add_u32_e32 v42, 0xd00, v64
	v_mov_b32_e32 v43, v1
	v_lshl_add_u64 v[42:43], v[42:43], 2, s[26:27]
	s_nop 1
	v_mov_b64_e32 v[102:103], v[198:199]
	v_mov_b64_e32 v[104:105], v[200:201]
	v_pk_mul_f32 v[42:43], v[82:83], v[100:101] op_sel_hi:[1,0]
	v_pk_add_f32 v[110:111], v[44:45], 1.0 op_sel_hi:[1,0]
	v_pk_mul_f32 v[44:45], v[84:85], v[100:101] op_sel_hi:[1,0]
	v_pk_fma_f32 v[42:43], v[42:43], v[34:35], v[38:39]
	v_pk_fma_f32 v[44:45], v[44:45], v[36:37], v[40:41]
	v_lshl_add_u64 v[82:83], s[2:3], 0, v[106:107]
	global_store_dwordx4 v[82:83], v[42:45], off
	v_pk_fma_f32 v[84:85], v[42:43], v[112:113], v[102:103]
	v_pk_fma_f32 v[82:83], v[44:45], v[110:111], v[104:105]
	v_med3_f32 v42, v84, s59, v250
	v_med3_f32 v43, v85, s59, v250
	v_mov_b32_e32 v44, v1
	v_cvt_pk_fp8_f32 v44, v42, v43
	v_med3_f32 v42, v82, s59, v250
	v_med3_f32 v43, v83, s59, v250
	v_cvt_pk_fp8_f32 v44, v42, v43 op_sel:[0,0,1]
	v_pk_mul_f32 v[42:43], v[76:77], v[98:99] op_sel_hi:[1,0]
	global_store_dword v0, v44, s[22:23]
	v_pk_mul_f32 v[44:45], v[74:75], v[98:99] op_sel_hi:[1,0]
	v_add_u32_e32 v0, 0x500, v64
	v_pk_fma_f32 v[34:35], v[34:35], v[44:45], v[38:39]
	v_pk_fma_f32 v[36:37], v[36:37], v[42:43], v[40:41]
	v_lshl_add_u64 v[38:39], v[0:1], 2, s[2:3]
	v_pk_fma_f32 v[44:45], v[112:113], v[34:35], v[102:103]
	global_store_dwordx4 v[38:39], v[34:37], off
	v_pk_fma_f32 v[42:43], v[110:111], v[36:37], v[104:105]
	v_add_u32_e32 v74, 0x1200, v64
	v_med3_f32 v34, v44, s59, v250
	v_med3_f32 v35, v45, s59, v250
	v_mov_b32_e32 v36, v1
	v_cvt_pk_fp8_f32 v36, v34, v35
	v_med3_f32 v34, v42, s59, v250
	v_med3_f32 v35, v43, s59, v250
	v_mov_b32_e32 v75, v1
	v_cvt_pk_fp8_f32 v36, v34, v35 op_sel:[0,0,1]
	v_lshl_add_u64 v[74:75], v[74:75], 2, s[26:27]
	global_store_dword v0, v36, s[22:23]
	s_nop 1
	v_mov_b64_e32 v[74:75], v[202:203]
	v_mov_b64_e32 v[76:77], v[204:205]
	v_add_u32_e32 v0, 0x200, v64
	v_lshlrev_b64 v[106:107], 2, v[0:1]
	v_lshl_add_u64 v[34:35], s[18:19], 0, v[106:107]
	v_lshl_add_u64 v[38:39], s[20:21], 0, v[106:107]
	s_nop 1
	v_mov_b64_e32 v[34:35], v[206:207]
	v_mov_b64_e32 v[36:37], v[208:209]
	v_pk_add_f32 v[112:113], v[74:75], 1.0 op_sel_hi:[1,0]
	v_add_u32_e32 v74, 0xe00, v64
	v_mov_b32_e32 v75, v1
	s_nop 1
	v_mov_b64_e32 v[38:39], v[210:211]
	v_mov_b64_e32 v[40:41], v[212:213]
	v_lshl_add_u64 v[74:75], v[74:75], 2, s[26:27]
	s_nop 1
	v_mov_b64_e32 v[102:103], v[214:215]
	v_mov_b64_e32 v[104:105], v[216:217]
	v_pk_add_f32 v[110:111], v[76:77], 1.0 op_sel_hi:[1,0]
	v_pk_mul_f32 v[74:75], v[80:81], v[100:101] op_sel_hi:[1,0]
	v_pk_mul_f32 v[76:77], v[78:79], v[100:101] op_sel_hi:[1,0]
	v_pk_fma_f32 v[78:79], v[74:75], v[36:37], v[40:41]
	v_pk_fma_f32 v[76:77], v[76:77], v[34:35], v[38:39]
	v_lshl_add_u64 v[74:75], s[2:3], 0, v[106:107]
	global_store_dwordx4 v[74:75], v[76:79], off
	v_pk_fma_f32 v[74:75], v[78:79], v[110:111], v[104:105]
	v_pk_fma_f32 v[34:35], v[68:69], v[34:35], v[38:39]
	v_pk_fma_f32 v[76:77], v[76:77], v[112:113], v[102:103]
	v_mov_b32_e32 v79, v1
	v_med3_f32 v65, v76, s59, v250
	v_med3_f32 v78, v77, s59, v250
	v_cvt_pk_fp8_f32 v79, v65, v78
	v_med3_f32 v65, v74, s59, v250
	v_med3_f32 v78, v75, s59, v250
	v_pk_fma_f32 v[36:37], v[70:71], v[36:37], v[40:41]
	v_cvt_pk_fp8_f32 v79, v65, v78 op_sel:[0,0,1]
	v_pk_fma_f32 v[40:41], v[34:35], v[112:113], v[102:103]
	global_store_dword v0, v79, s[22:23]
	v_add_u32_e32 v0, 0x600, v64
	v_lshl_add_u64 v[38:39], v[0:1], 2, s[2:3]
	global_store_dwordx4 v[38:39], v[34:37], off
	v_pk_fma_f32 v[38:39], v[36:37], v[110:111], v[104:105]
	s_nop 0
	v_med3_f32 v34, v40, s59, v250
	v_med3_f32 v35, v41, s59, v250
	v_mov_b32_e32 v36, v1
	v_cvt_pk_fp8_f32 v36, v34, v35
	v_med3_f32 v34, v38, s59, v250
	v_med3_f32 v35, v39, s59, v250
	v_cvt_pk_fp8_f32 v36, v34, v35 op_sel:[0,0,1]
	global_store_dword v0, v36, s[22:23]
	v_add_u32_e32 v0, 0x300, v64
	v_lshlrev_b64 v[106:107], 2, v[0:1]
	v_lshl_add_u64 v[68:69], s[20:21], 0, v[106:107]
	s_nop 1
	v_mov_b64_e32 v[78:79], v[114:115]
	v_mov_b64_e32 v[80:81], v[116:117]
	v_add_u32_e32 v68, 0x1300, v64
	v_mov_b32_e32 v69, v1
	v_lshl_add_u64 v[68:69], v[68:69], 2, s[26:27]
	s_nop 1
	v_mov_b64_e32 v[68:69], v[218:219]
	v_mov_b64_e32 v[70:71], v[220:221]
	v_lshl_add_u64 v[34:35], s[18:19], 0, v[106:107]
	s_nop 1
	v_mov_b64_e32 v[34:35], v[222:223]
	v_mov_b64_e32 v[36:37], v[224:225]
	v_pk_add_f32 v[112:113], v[68:69], 1.0 op_sel_hi:[1,0]
	v_add_u32_e32 v68, 0xf00, v64
	v_mov_b32_e32 v69, v1
	v_lshl_add_u64 v[68:69], v[68:69], 2, s[26:27]
	s_nop 1
	v_mov_b64_e32 v[102:103], v[118:119]
	v_mov_b64_e32 v[104:105], v[120:121]
	v_pk_add_f32 v[110:111], v[70:71], 1.0 op_sel_hi:[1,0]
	v_pk_mul_f32 v[70:71], v[94:95], v[100:101] op_sel_hi:[1,0]
	v_pk_mul_f32 v[68:69], v[96:97], v[100:101] op_sel_hi:[1,0]
	v_pk_fma_f32 v[94:95], v[70:71], v[34:35], v[78:79]
	v_pk_fma_f32 v[96:97], v[68:69], v[36:37], v[80:81]
	v_lshl_add_u64 v[68:69], s[2:3], 0, v[106:107]
	global_store_dwordx4 v[68:69], v[94:97], off
	v_pk_fma_f32 v[78:79], v[92:93], v[34:35], v[78:79]
	v_pk_fma_f32 v[80:81], v[90:91], v[36:37], v[80:81]
	v_pk_fma_f32 v[70:71], v[94:95], v[112:113], v[102:103]
	s_nop 0
	v_med3_f32 v65, v70, s59, v250
	v_med3_f32 v94, v71, s59, v250
	v_mov_b32_e32 v95, v1
	v_cvt_pk_fp8_f32 v95, v65, v94
	v_pk_fma_f32 v[68:69], v[96:97], v[110:111], v[104:105]
	v_pk_fma_f32 v[36:37], v[78:79], v[112:113], v[102:103]
	v_med3_f32 v65, v68, s59, v250
	v_med3_f32 v94, v69, s59, v250
	v_cvt_pk_fp8_f32 v95, v65, v94 op_sel:[0,0,1]
	v_med3_f32 v65, v36, s59, v250
	global_store_dword v0, v95, s[22:23]
	v_add_u32_e32 v0, 0x700, v64
	v_lshl_add_u64 v[34:35], v[0:1], 2, s[2:3]
	global_store_dwordx4 v[34:35], v[78:81], off
	v_pk_fma_f32 v[34:35], v[80:81], v[110:111], v[104:105]
	s_nop 0
	v_med3_f32 v78, v37, s59, v250
	v_mov_b32_e32 v79, v1
	v_cvt_pk_fp8_f32 v79, v65, v78
	v_med3_f32 v65, v34, s59, v250
	v_med3_f32 v78, v35, s59, v250
	v_cvt_pk_fp8_f32 v79, v65, v78 op_sel:[0,0,1]
	global_store_dword v0, v79, s[22:23]
	v_readlane_b32 s14, v254, 49
	s_add_i32 s24, s24, s14
	v_readlane_b32 s15, v254, 50
	s_cmp_ge_i32 s24, s41
	s_cselect_b64 s[14:15], -1, 0
	s_and_b64 vcc, exec, s[14:15]
	s_cbranch_vccnz .LBB0_1429
	v_readlane_b32 s26, v254, 57
	v_readlane_b32 s27, v254, 58
	v_mov_b32_e32 v0, v108
	s_mov_b64 s[28:29], -1
	s_and_b64 vcc, exec, s[26:27]
	s_cbranch_vccz .LBB0_1416
	s_ashr_i32 s25, s24, 31
	s_lshl_b64 s[26:27], s[24:25], 12
	s_add_u32 s26, s39, s26
	s_addc_u32 s27, s40, s27
	s_mov_b64 s[28:29], 0
